# v41 + SchedH epilogue fast paths: straight-line sigmoid (kinds 0/1) and ring-pipelined t2 (kind 3) instead of the per-block kind switch
# speedup vs baseline: 1.0007x; 1.0007x over previous
.LBB0_1047:
	v_readlane_b32 s84, v255, 0
	v_readlane_b32 s85, v255, 1
	v_readlane_b32 s86, v255, 2
	v_readlane_b32 s87, v255, 3
	v_readlane_b32 s88, v255, 4
	v_readlane_b32 s89, v255, 5
	v_readlane_b32 s90, v255, 6
	v_readlane_b32 s91, v255, 7
	s_mov_b64 s[84:85], s[88:89]
	s_cmpk_lt_i32 s4, 0x80
	s_mov_b64 s[86:87], s[90:91]
	s_cselect_b32 s43, s87, s37
	s_cselect_b32 s42, s86, s36
	s_cselect_b32 s45, s25, s39
	s_cselect_b32 s44, s24, s38
	s_lshl_b32 s4, s4, 19
	s_lshl_b32 s5, s28, 9
	s_add_i32 s28, s4, s5
	s_cmp_gt_i32 s63, 1
	s_cselect_b64 s[34:35], -1, 0
	v_add_u32_e32 v136, s28, v145
	s_cmp_eq_u32 s63, 3
	s_cbranch_scc1 .Lsh_k3
	s_cmp_lt_u32 s63, 2
	s_cbranch_scc1 .Lsh_k01
	s_mov_b64 s[4:5], -1
	s_and_b64 vcc, exec, s[34:35]
	s_cbranch_vccz .LBB0_1053
	s_cmp_lg_u32 s63, 3
	v_lshl_add_u64 v[142:143], s[44:45], 0, v[136:137]
	s_cbranch_scc0 .LBB0_1050
	v_lshl_add_u64 v[160:161], s[42:43], 0, v[136:137]
	global_load_dwordx4 v[156:159], v[142:143], off
	s_mov_b64 s[4:5], 0
	global_load_dwordx4 v[160:163], v[160:161], off
	s_waitcnt vmcnt(0)
	v_cvt_f32_f16_e32 v164, v157
	v_cvt_f32_f16_sdwa v165, v157 dst_sel:DWORD dst_unused:UNUSED_PAD src0_sel:WORD_1
	v_cvt_f32_f16_e32 v166, v156
	v_cvt_f32_f16_sdwa v167, v156 dst_sel:DWORD dst_unused:UNUSED_PAD src0_sel:WORD_1
	v_cvt_f32_f16_e32 v156, v159
	v_cvt_f32_f16_sdwa v157, v159 dst_sel:DWORD dst_unused:UNUSED_PAD src0_sel:WORD_1
	v_cvt_f32_f16_e32 v168, v158
	v_cvt_f32_f16_sdwa v169, v158 dst_sel:DWORD dst_unused:UNUSED_PAD src0_sel:WORD_1
	v_cvt_f32_f16_e32 v158, v161
	v_cvt_f32_f16_sdwa v159, v161 dst_sel:DWORD dst_unused:UNUSED_PAD src0_sel:WORD_1
	v_cvt_f32_f16_e32 v170, v160
	v_cvt_f32_f16_sdwa v171, v160 dst_sel:DWORD dst_unused:UNUSED_PAD src0_sel:WORD_1
	v_cvt_f32_f16_e32 v160, v163
	v_cvt_f32_f16_e32 v172, v162
	v_cvt_f32_f16_sdwa v173, v162 dst_sel:DWORD dst_unused:UNUSED_PAD src0_sel:WORD_1
	v_cvt_f32_f16_sdwa v161, v163 dst_sel:DWORD dst_unused:UNUSED_PAD src0_sel:WORD_1
	v_pk_fma_f32 v[162:163], v[124:125], v[170:171], v[166:167]
	v_pk_fma_f32 v[164:165], v[126:127], v[158:159], v[164:165]
	v_pk_fma_f32 v[166:167], v[120:121], v[172:173], v[168:169]
	v_pk_fma_f32 v[156:157], v[122:123], v[160:161], v[156:157]
	v_cvt_pk_f16_f32 v158, v166, v167
	v_cvt_pk_f16_f32 v159, v156, v157
	v_cvt_pk_f16_f32 v157, v164, v165
	v_cvt_pk_f16_f32 v156, v162, v163
	v_lshl_add_u64 v[160:161], s[22:23], 0, v[136:137]
	global_store_dwordx4 v[160:161], v[156:159], off sc1
	s_nop 1

.Lsh_k01:
	s_cmp_eq_u32 s63, 0
	s_cselect_b32 s5, s43, s45
	s_cselect_b32 s4, s42, s44
	v_mov_b32_e32 v156, v136
	v_add_u32_e32 v157, 0x8000, v136
	v_add_u32_e32 v158, 0x10000, v136
	v_add_u32_e32 v159, 0x18000, v136
	v_add_u32_e32 v160, 0x40000, v136
	v_add_u32_e32 v161, 0x48000, v136
	v_add_u32_e32 v162, 0x50000, v136
	v_add_u32_e32 v163, 0x58000, v136
	v_mul_f32_e32 v124, 0xbfb8aa3b, v124
	v_mul_f32_e32 v120, 0xbfb8aa3b, v120
	v_mul_f32_e32 v125, 0xbfb8aa3b, v125
	v_mul_f32_e32 v121, 0xbfb8aa3b, v121
	v_mul_f32_e32 v126, 0xbfb8aa3b, v126
	v_mul_f32_e32 v122, 0xbfb8aa3b, v122
	v_mul_f32_e32 v123, 0xbfb8aa3b, v123
	v_mul_f32_e32 v127, 0xbfb8aa3b, v127
	v_exp_f32_e32 v124, v124
	v_exp_f32_e32 v120, v120
	v_exp_f32_e32 v125, v125
	v_exp_f32_e32 v121, v121
	v_exp_f32_e32 v126, v126
	v_exp_f32_e32 v122, v122
	v_exp_f32_e32 v123, v123
	v_exp_f32_e32 v127, v127
	v_add_f32_e32 v124, 1.0, v124
	v_add_f32_e32 v120, 1.0, v120
	v_add_f32_e32 v125, 1.0, v125
	v_add_f32_e32 v121, 1.0, v121
	v_add_f32_e32 v126, 1.0, v126
	v_add_f32_e32 v122, 1.0, v122
	v_add_f32_e32 v123, 1.0, v123
	v_add_f32_e32 v127, 1.0, v127
	v_rcp_f32_e32 v124, v124
	v_rcp_f32_e32 v120, v120
	v_rcp_f32_e32 v121, v121
	v_rcp_f32_e32 v126, v126
	v_rcp_f32_e32 v122, v122
	v_rcp_f32_e32 v123, v123
	v_rcp_f32_e32 v127, v127
	v_rcp_f32_e32 v125, v125
	s_nop 0
	v_cvt_pk_f16_f32 v123, v122, v123
	v_cvt_pk_f16_f32 v122, v120, v121
	v_cvt_pk_f16_f32 v121, v126, v127
	v_cvt_pk_f16_f32 v120, v124, v125
	global_store_dwordx4 v156, v[120:123], s[4:5]
	v_mul_f32_e32 v116, 0xbfb8aa3b, v116
	v_mul_f32_e32 v112, 0xbfb8aa3b, v112
	v_mul_f32_e32 v117, 0xbfb8aa3b, v117
	v_mul_f32_e32 v113, 0xbfb8aa3b, v113
	v_mul_f32_e32 v118, 0xbfb8aa3b, v118
	v_mul_f32_e32 v114, 0xbfb8aa3b, v114
	v_mul_f32_e32 v115, 0xbfb8aa3b, v115
	v_mul_f32_e32 v119, 0xbfb8aa3b, v119
	v_exp_f32_e32 v116, v116
	v_exp_f32_e32 v112, v112
	v_exp_f32_e32 v117, v117
	v_exp_f32_e32 v113, v113
	v_exp_f32_e32 v118, v118
	v_exp_f32_e32 v114, v114
	v_exp_f32_e32 v115, v115
	v_exp_f32_e32 v119, v119
	v_add_f32_e32 v116, 1.0, v116
	v_add_f32_e32 v112, 1.0, v112
	v_add_f32_e32 v117, 1.0, v117
	v_add_f32_e32 v113, 1.0, v113
	v_add_f32_e32 v118, 1.0, v118
	v_add_f32_e32 v114, 1.0, v114
	v_add_f32_e32 v115, 1.0, v115
	v_add_f32_e32 v119, 1.0, v119
	v_rcp_f32_e32 v116, v116
	v_rcp_f32_e32 v112, v112
	v_rcp_f32_e32 v113, v113
	v_rcp_f32_e32 v118, v118
	v_rcp_f32_e32 v114, v114
	v_rcp_f32_e32 v115, v115
	v_rcp_f32_e32 v119, v119
	v_rcp_f32_e32 v117, v117
	s_nop 0
	v_cvt_pk_f16_f32 v115, v114, v115
	v_cvt_pk_f16_f32 v114, v112, v113
	v_cvt_pk_f16_f32 v113, v118, v119
	v_cvt_pk_f16_f32 v112, v116, v117
	global_store_dwordx4 v156, v[112:115], s[4:5] offset:256
	v_mul_f32_e32 v108, 0xbfb8aa3b, v108
	v_mul_f32_e32 v104, 0xbfb8aa3b, v104
	v_mul_f32_e32 v109, 0xbfb8aa3b, v109
	v_mul_f32_e32 v105, 0xbfb8aa3b, v105
	v_mul_f32_e32 v110, 0xbfb8aa3b, v110
	v_mul_f32_e32 v106, 0xbfb8aa3b, v106
	v_mul_f32_e32 v107, 0xbfb8aa3b, v107
	v_mul_f32_e32 v111, 0xbfb8aa3b, v111
	v_exp_f32_e32 v108, v108
	v_exp_f32_e32 v104, v104
	v_exp_f32_e32 v109, v109
	v_exp_f32_e32 v105, v105
	v_exp_f32_e32 v110, v110
	v_exp_f32_e32 v106, v106
	v_exp_f32_e32 v107, v107
	v_exp_f32_e32 v111, v111
	v_add_f32_e32 v108, 1.0, v108
	v_add_f32_e32 v104, 1.0, v104
	v_add_f32_e32 v109, 1.0, v109
	v_add_f32_e32 v105, 1.0, v105
	v_add_f32_e32 v110, 1.0, v110
	v_add_f32_e32 v106, 1.0, v106
	v_add_f32_e32 v107, 1.0, v107
	v_add_f32_e32 v111, 1.0, v111
	v_rcp_f32_e32 v108, v108
	v_rcp_f32_e32 v104, v104
	v_rcp_f32_e32 v105, v105
	v_rcp_f32_e32 v110, v110
	v_rcp_f32_e32 v106, v106
	v_rcp_f32_e32 v107, v107
	v_rcp_f32_e32 v111, v111
	v_rcp_f32_e32 v109, v109
	s_nop 0
	v_cvt_pk_f16_f32 v107, v106, v107
	v_cvt_pk_f16_f32 v106, v104, v105
	v_cvt_pk_f16_f32 v105, v110, v111
	v_cvt_pk_f16_f32 v104, v108, v109
	global_store_dwordx4 v157, v[104:107], s[4:5]
	v_mul_f32_e32 v100, 0xbfb8aa3b, v100
	v_mul_f32_e32 v96, 0xbfb8aa3b, v96
	v_mul_f32_e32 v101, 0xbfb8aa3b, v101
	v_mul_f32_e32 v97, 0xbfb8aa3b, v97
	v_mul_f32_e32 v102, 0xbfb8aa3b, v102
	v_mul_f32_e32 v98, 0xbfb8aa3b, v98
	v_mul_f32_e32 v99, 0xbfb8aa3b, v99
	v_mul_f32_e32 v103, 0xbfb8aa3b, v103
	v_exp_f32_e32 v100, v100
	v_exp_f32_e32 v96, v96
	v_exp_f32_e32 v101, v101
	v_exp_f32_e32 v97, v97
	v_exp_f32_e32 v102, v102
	v_exp_f32_e32 v98, v98
	v_exp_f32_e32 v99, v99
	v_exp_f32_e32 v103, v103
	v_add_f32_e32 v100, 1.0, v100
	v_add_f32_e32 v96, 1.0, v96
	v_add_f32_e32 v101, 1.0, v101
	v_add_f32_e32 v97, 1.0, v97
	v_add_f32_e32 v102, 1.0, v102
	v_add_f32_e32 v98, 1.0, v98
	v_add_f32_e32 v99, 1.0, v99
	v_add_f32_e32 v103, 1.0, v103
	v_rcp_f32_e32 v100, v100
	v_rcp_f32_e32 v96, v96
	v_rcp_f32_e32 v97, v97
	v_rcp_f32_e32 v102, v102
	v_rcp_f32_e32 v98, v98
	v_rcp_f32_e32 v99, v99
	v_rcp_f32_e32 v103, v103
	v_rcp_f32_e32 v101, v101
	s_nop 0
	v_cvt_pk_f16_f32 v99, v98, v99
	v_cvt_pk_f16_f32 v98, v96, v97
	v_cvt_pk_f16_f32 v97, v102, v103
	v_cvt_pk_f16_f32 v96, v100, v101
	global_store_dwordx4 v157, v[96:99], s[4:5] offset:256
	v_mul_f32_e32 v92, 0xbfb8aa3b, v92
	v_mul_f32_e32 v88, 0xbfb8aa3b, v88
	v_mul_f32_e32 v93, 0xbfb8aa3b, v93
	v_mul_f32_e32 v89, 0xbfb8aa3b, v89
	v_mul_f32_e32 v94, 0xbfb8aa3b, v94
	v_mul_f32_e32 v90, 0xbfb8aa3b, v90
	v_mul_f32_e32 v91, 0xbfb8aa3b, v91
	v_mul_f32_e32 v95, 0xbfb8aa3b, v95
	v_exp_f32_e32 v92, v92
	v_exp_f32_e32 v88, v88
	v_exp_f32_e32 v93, v93
	v_exp_f32_e32 v89, v89
	v_exp_f32_e32 v94, v94
	v_exp_f32_e32 v90, v90
	v_exp_f32_e32 v91, v91
	v_exp_f32_e32 v95, v95
	v_add_f32_e32 v92, 1.0, v92
	v_add_f32_e32 v88, 1.0, v88
	v_add_f32_e32 v93, 1.0, v93
	v_add_f32_e32 v89, 1.0, v89
	v_add_f32_e32 v94, 1.0, v94
	v_add_f32_e32 v90, 1.0, v90
	v_add_f32_e32 v91, 1.0, v91
	v_add_f32_e32 v95, 1.0, v95
	v_rcp_f32_e32 v92, v92
	v_rcp_f32_e32 v88, v88
	v_rcp_f32_e32 v89, v89
	v_rcp_f32_e32 v94, v94
	v_rcp_f32_e32 v90, v90
	v_rcp_f32_e32 v91, v91
	v_rcp_f32_e32 v95, v95
	v_rcp_f32_e32 v93, v93
	s_nop 0
	v_cvt_pk_f16_f32 v91, v90, v91
	v_cvt_pk_f16_f32 v90, v88, v89
	v_cvt_pk_f16_f32 v89, v94, v95
	v_cvt_pk_f16_f32 v88, v92, v93
	global_store_dwordx4 v158, v[88:91], s[4:5]
	v_mul_f32_e32 v84, 0xbfb8aa3b, v84
	v_mul_f32_e32 v80, 0xbfb8aa3b, v80
	v_mul_f32_e32 v85, 0xbfb8aa3b, v85
	v_mul_f32_e32 v81, 0xbfb8aa3b, v81
	v_mul_f32_e32 v86, 0xbfb8aa3b, v86
	v_mul_f32_e32 v82, 0xbfb8aa3b, v82
	v_mul_f32_e32 v83, 0xbfb8aa3b, v83
	v_mul_f32_e32 v87, 0xbfb8aa3b, v87
	v_exp_f32_e32 v84, v84
	v_exp_f32_e32 v80, v80
	v_exp_f32_e32 v85, v85
	v_exp_f32_e32 v81, v81
	v_exp_f32_e32 v86, v86
	v_exp_f32_e32 v82, v82
	v_exp_f32_e32 v83, v83
	v_exp_f32_e32 v87, v87
	v_add_f32_e32 v84, 1.0, v84
	v_add_f32_e32 v80, 1.0, v80
	v_add_f32_e32 v85, 1.0, v85
	v_add_f32_e32 v81, 1.0, v81
	v_add_f32_e32 v86, 1.0, v86
	v_add_f32_e32 v82, 1.0, v82
	v_add_f32_e32 v83, 1.0, v83
	v_add_f32_e32 v87, 1.0, v87
	v_rcp_f32_e32 v84, v84
	v_rcp_f32_e32 v80, v80
	v_rcp_f32_e32 v81, v81
	v_rcp_f32_e32 v86, v86
	v_rcp_f32_e32 v82, v82
	v_rcp_f32_e32 v83, v83
	v_rcp_f32_e32 v87, v87
	v_rcp_f32_e32 v85, v85
	s_nop 0
	v_cvt_pk_f16_f32 v83, v82, v83
	v_cvt_pk_f16_f32 v82, v80, v81
	v_cvt_pk_f16_f32 v81, v86, v87
	v_cvt_pk_f16_f32 v80, v84, v85
	global_store_dwordx4 v158, v[80:83], s[4:5] offset:256
	v_mul_f32_e32 v76, 0xbfb8aa3b, v76
	v_mul_f32_e32 v72, 0xbfb8aa3b, v72
	v_mul_f32_e32 v77, 0xbfb8aa3b, v77
	v_mul_f32_e32 v73, 0xbfb8aa3b, v73
	v_mul_f32_e32 v78, 0xbfb8aa3b, v78
	v_mul_f32_e32 v74, 0xbfb8aa3b, v74
	v_mul_f32_e32 v75, 0xbfb8aa3b, v75
	v_mul_f32_e32 v79, 0xbfb8aa3b, v79
	v_exp_f32_e32 v76, v76
	v_exp_f32_e32 v72, v72
	v_exp_f32_e32 v77, v77
	v_exp_f32_e32 v73, v73
	v_exp_f32_e32 v78, v78
	v_exp_f32_e32 v74, v74
	v_exp_f32_e32 v75, v75
	v_exp_f32_e32 v79, v79
	v_add_f32_e32 v76, 1.0, v76
	v_add_f32_e32 v72, 1.0, v72
	v_add_f32_e32 v77, 1.0, v77
	v_add_f32_e32 v73, 1.0, v73
	v_add_f32_e32 v78, 1.0, v78
	v_add_f32_e32 v74, 1.0, v74
	v_add_f32_e32 v75, 1.0, v75
	v_add_f32_e32 v79, 1.0, v79
	v_rcp_f32_e32 v76, v76
	v_rcp_f32_e32 v72, v72
	v_rcp_f32_e32 v73, v73
	v_rcp_f32_e32 v78, v78
	v_rcp_f32_e32 v74, v74
	v_rcp_f32_e32 v75, v75
	v_rcp_f32_e32 v79, v79
	v_rcp_f32_e32 v77, v77
	s_nop 0
	v_cvt_pk_f16_f32 v75, v74, v75
	v_cvt_pk_f16_f32 v74, v72, v73
	v_cvt_pk_f16_f32 v73, v78, v79
	v_cvt_pk_f16_f32 v72, v76, v77
	global_store_dwordx4 v159, v[72:75], s[4:5]
	v_mul_f32_e32 v68, 0xbfb8aa3b, v68
	v_mul_f32_e32 v64, 0xbfb8aa3b, v64
	v_mul_f32_e32 v69, 0xbfb8aa3b, v69
	v_mul_f32_e32 v65, 0xbfb8aa3b, v65
	v_mul_f32_e32 v70, 0xbfb8aa3b, v70
	v_mul_f32_e32 v66, 0xbfb8aa3b, v66
	v_mul_f32_e32 v67, 0xbfb8aa3b, v67
	v_mul_f32_e32 v71, 0xbfb8aa3b, v71
	v_exp_f32_e32 v68, v68
	v_exp_f32_e32 v64, v64
	v_exp_f32_e32 v69, v69
	v_exp_f32_e32 v65, v65
	v_exp_f32_e32 v70, v70
	v_exp_f32_e32 v66, v66
	v_exp_f32_e32 v67, v67
	v_exp_f32_e32 v71, v71
	v_add_f32_e32 v68, 1.0, v68
	v_add_f32_e32 v64, 1.0, v64
	v_add_f32_e32 v69, 1.0, v69
	v_add_f32_e32 v65, 1.0, v65
	v_add_f32_e32 v70, 1.0, v70
	v_add_f32_e32 v66, 1.0, v66
	v_add_f32_e32 v67, 1.0, v67
	v_add_f32_e32 v71, 1.0, v71
	v_rcp_f32_e32 v68, v68
	v_rcp_f32_e32 v64, v64
	v_rcp_f32_e32 v65, v65
	v_rcp_f32_e32 v70, v70
	v_rcp_f32_e32 v66, v66
	v_rcp_f32_e32 v67, v67
	v_rcp_f32_e32 v71, v71
	v_rcp_f32_e32 v69, v69
	s_nop 0
	v_cvt_pk_f16_f32 v67, v66, v67
	v_cvt_pk_f16_f32 v66, v64, v65
	v_cvt_pk_f16_f32 v65, v70, v71
	v_cvt_pk_f16_f32 v64, v68, v69
	global_store_dwordx4 v159, v[64:67], s[4:5] offset:256
	v_mul_f32_e32 v60, 0xbfb8aa3b, v60
	v_mul_f32_e32 v56, 0xbfb8aa3b, v56
	v_mul_f32_e32 v61, 0xbfb8aa3b, v61
	v_mul_f32_e32 v57, 0xbfb8aa3b, v57
	v_mul_f32_e32 v62, 0xbfb8aa3b, v62
	v_mul_f32_e32 v58, 0xbfb8aa3b, v58
	v_mul_f32_e32 v59, 0xbfb8aa3b, v59
	v_mul_f32_e32 v63, 0xbfb8aa3b, v63
	v_exp_f32_e32 v60, v60
	v_exp_f32_e32 v56, v56
	v_exp_f32_e32 v61, v61
	v_exp_f32_e32 v57, v57
	v_exp_f32_e32 v62, v62
	v_exp_f32_e32 v58, v58
	v_exp_f32_e32 v59, v59
	v_exp_f32_e32 v63, v63
	v_add_f32_e32 v60, 1.0, v60
	v_add_f32_e32 v56, 1.0, v56
	v_add_f32_e32 v61, 1.0, v61
	v_add_f32_e32 v57, 1.0, v57
	v_add_f32_e32 v62, 1.0, v62
	v_add_f32_e32 v58, 1.0, v58
	v_add_f32_e32 v59, 1.0, v59
	v_add_f32_e32 v63, 1.0, v63
	v_rcp_f32_e32 v60, v60
	v_rcp_f32_e32 v56, v56
	v_rcp_f32_e32 v57, v57
	v_rcp_f32_e32 v62, v62
	v_rcp_f32_e32 v58, v58
	v_rcp_f32_e32 v59, v59
	v_rcp_f32_e32 v63, v63
	v_rcp_f32_e32 v61, v61
	s_nop 0
	v_cvt_pk_f16_f32 v59, v58, v59
	v_cvt_pk_f16_f32 v58, v56, v57
	v_cvt_pk_f16_f32 v57, v62, v63
	v_cvt_pk_f16_f32 v56, v60, v61
	global_store_dwordx4 v160, v[56:59], s[4:5]
	v_mul_f32_e32 v52, 0xbfb8aa3b, v52
	v_mul_f32_e32 v48, 0xbfb8aa3b, v48
	v_mul_f32_e32 v53, 0xbfb8aa3b, v53
	v_mul_f32_e32 v49, 0xbfb8aa3b, v49
	v_mul_f32_e32 v54, 0xbfb8aa3b, v54
	v_mul_f32_e32 v50, 0xbfb8aa3b, v50
	v_mul_f32_e32 v51, 0xbfb8aa3b, v51
	v_mul_f32_e32 v55, 0xbfb8aa3b, v55
	v_exp_f32_e32 v52, v52
	v_exp_f32_e32 v48, v48
	v_exp_f32_e32 v53, v53
	v_exp_f32_e32 v49, v49
	v_exp_f32_e32 v54, v54
	v_exp_f32_e32 v50, v50
	v_exp_f32_e32 v51, v51
	v_exp_f32_e32 v55, v55
	v_add_f32_e32 v52, 1.0, v52
	v_add_f32_e32 v48, 1.0, v48
	v_add_f32_e32 v53, 1.0, v53
	v_add_f32_e32 v49, 1.0, v49
	v_add_f32_e32 v54, 1.0, v54
	v_add_f32_e32 v50, 1.0, v50
	v_add_f32_e32 v51, 1.0, v51
	v_add_f32_e32 v55, 1.0, v55
	v_rcp_f32_e32 v52, v52
	v_rcp_f32_e32 v48, v48
	v_rcp_f32_e32 v49, v49
	v_rcp_f32_e32 v54, v54
	v_rcp_f32_e32 v50, v50
	v_rcp_f32_e32 v51, v51
	v_rcp_f32_e32 v55, v55
	v_rcp_f32_e32 v53, v53
	s_nop 0
	v_cvt_pk_f16_f32 v51, v50, v51
	v_cvt_pk_f16_f32 v50, v48, v49
	v_cvt_pk_f16_f32 v49, v54, v55
	v_cvt_pk_f16_f32 v48, v52, v53
	global_store_dwordx4 v160, v[48:51], s[4:5] offset:256
	v_mul_f32_e32 v44, 0xbfb8aa3b, v44
	v_mul_f32_e32 v40, 0xbfb8aa3b, v40
	v_mul_f32_e32 v45, 0xbfb8aa3b, v45
	v_mul_f32_e32 v41, 0xbfb8aa3b, v41
	v_mul_f32_e32 v46, 0xbfb8aa3b, v46
	v_mul_f32_e32 v42, 0xbfb8aa3b, v42
	v_mul_f32_e32 v43, 0xbfb8aa3b, v43
	v_mul_f32_e32 v47, 0xbfb8aa3b, v47
	v_exp_f32_e32 v44, v44
	v_exp_f32_e32 v40, v40
	v_exp_f32_e32 v45, v45
	v_exp_f32_e32 v41, v41
	v_exp_f32_e32 v46, v46
	v_exp_f32_e32 v42, v42
	v_exp_f32_e32 v43, v43
	v_exp_f32_e32 v47, v47
	v_add_f32_e32 v44, 1.0, v44
	v_add_f32_e32 v40, 1.0, v40
	v_add_f32_e32 v45, 1.0, v45
	v_add_f32_e32 v41, 1.0, v41
	v_add_f32_e32 v46, 1.0, v46
	v_add_f32_e32 v42, 1.0, v42
	v_add_f32_e32 v43, 1.0, v43
	v_add_f32_e32 v47, 1.0, v47
	v_rcp_f32_e32 v44, v44
	v_rcp_f32_e32 v40, v40
	v_rcp_f32_e32 v41, v41
	v_rcp_f32_e32 v46, v46
	v_rcp_f32_e32 v42, v42
	v_rcp_f32_e32 v43, v43
	v_rcp_f32_e32 v47, v47
	v_rcp_f32_e32 v45, v45
	s_nop 0
	v_cvt_pk_f16_f32 v43, v42, v43
	v_cvt_pk_f16_f32 v42, v40, v41
	v_cvt_pk_f16_f32 v41, v46, v47
	v_cvt_pk_f16_f32 v40, v44, v45
	global_store_dwordx4 v161, v[40:43], s[4:5]
	v_mul_f32_e32 v36, 0xbfb8aa3b, v36
	v_mul_f32_e32 v32, 0xbfb8aa3b, v32
	v_mul_f32_e32 v37, 0xbfb8aa3b, v37
	v_mul_f32_e32 v33, 0xbfb8aa3b, v33
	v_mul_f32_e32 v38, 0xbfb8aa3b, v38
	v_mul_f32_e32 v34, 0xbfb8aa3b, v34
	v_mul_f32_e32 v35, 0xbfb8aa3b, v35
	v_mul_f32_e32 v39, 0xbfb8aa3b, v39
	v_exp_f32_e32 v36, v36
	v_exp_f32_e32 v32, v32
	v_exp_f32_e32 v37, v37
	v_exp_f32_e32 v33, v33
	v_exp_f32_e32 v38, v38
	v_exp_f32_e32 v34, v34
	v_exp_f32_e32 v35, v35
	v_exp_f32_e32 v39, v39
	v_add_f32_e32 v36, 1.0, v36
	v_add_f32_e32 v32, 1.0, v32
	v_add_f32_e32 v37, 1.0, v37
	v_add_f32_e32 v33, 1.0, v33
	v_add_f32_e32 v38, 1.0, v38
	v_add_f32_e32 v34, 1.0, v34
	v_add_f32_e32 v35, 1.0, v35
	v_add_f32_e32 v39, 1.0, v39
	v_rcp_f32_e32 v36, v36
	v_rcp_f32_e32 v32, v32
	v_rcp_f32_e32 v33, v33
	v_rcp_f32_e32 v38, v38
	v_rcp_f32_e32 v34, v34
	v_rcp_f32_e32 v35, v35
	v_rcp_f32_e32 v39, v39
	v_rcp_f32_e32 v37, v37
	s_nop 0
	v_cvt_pk_f16_f32 v35, v34, v35
	v_cvt_pk_f16_f32 v34, v32, v33
	v_cvt_pk_f16_f32 v33, v38, v39
	v_cvt_pk_f16_f32 v32, v36, v37
	global_store_dwordx4 v161, v[32:35], s[4:5] offset:256
	v_mul_f32_e32 v28, 0xbfb8aa3b, v28
	v_mul_f32_e32 v24, 0xbfb8aa3b, v24
	v_mul_f32_e32 v29, 0xbfb8aa3b, v29
	v_mul_f32_e32 v25, 0xbfb8aa3b, v25
	v_mul_f32_e32 v30, 0xbfb8aa3b, v30
	v_mul_f32_e32 v26, 0xbfb8aa3b, v26
	v_mul_f32_e32 v27, 0xbfb8aa3b, v27
	v_mul_f32_e32 v31, 0xbfb8aa3b, v31
	v_exp_f32_e32 v28, v28
	v_exp_f32_e32 v24, v24
	v_exp_f32_e32 v29, v29
	v_exp_f32_e32 v25, v25
	v_exp_f32_e32 v30, v30
	v_exp_f32_e32 v26, v26
	v_exp_f32_e32 v27, v27
	v_exp_f32_e32 v31, v31
	v_add_f32_e32 v28, 1.0, v28
	v_add_f32_e32 v24, 1.0, v24
	v_add_f32_e32 v29, 1.0, v29
	v_add_f32_e32 v25, 1.0, v25
	v_add_f32_e32 v30, 1.0, v30
	v_add_f32_e32 v26, 1.0, v26
	v_add_f32_e32 v27, 1.0, v27
	v_add_f32_e32 v31, 1.0, v31
	v_rcp_f32_e32 v28, v28
	v_rcp_f32_e32 v24, v24
	v_rcp_f32_e32 v25, v25
	v_rcp_f32_e32 v30, v30
	v_rcp_f32_e32 v26, v26
	v_rcp_f32_e32 v27, v27
	v_rcp_f32_e32 v31, v31
	v_rcp_f32_e32 v29, v29
	s_nop 0
	v_cvt_pk_f16_f32 v27, v26, v27
	v_cvt_pk_f16_f32 v26, v24, v25
	v_cvt_pk_f16_f32 v25, v30, v31
	v_cvt_pk_f16_f32 v24, v28, v29
	global_store_dwordx4 v162, v[24:27], s[4:5]
	v_mul_f32_e32 v20, 0xbfb8aa3b, v20
	v_mul_f32_e32 v16, 0xbfb8aa3b, v16
	v_mul_f32_e32 v21, 0xbfb8aa3b, v21
	v_mul_f32_e32 v17, 0xbfb8aa3b, v17
	v_mul_f32_e32 v22, 0xbfb8aa3b, v22
	v_mul_f32_e32 v18, 0xbfb8aa3b, v18
	v_mul_f32_e32 v19, 0xbfb8aa3b, v19
	v_mul_f32_e32 v23, 0xbfb8aa3b, v23
	v_exp_f32_e32 v20, v20
	v_exp_f32_e32 v16, v16
	v_exp_f32_e32 v21, v21
	v_exp_f32_e32 v17, v17
	v_exp_f32_e32 v22, v22
	v_exp_f32_e32 v18, v18
	v_exp_f32_e32 v19, v19
	v_exp_f32_e32 v23, v23
	v_add_f32_e32 v20, 1.0, v20
	v_add_f32_e32 v16, 1.0, v16
	v_add_f32_e32 v21, 1.0, v21
	v_add_f32_e32 v17, 1.0, v17
	v_add_f32_e32 v22, 1.0, v22
	v_add_f32_e32 v18, 1.0, v18
	v_add_f32_e32 v19, 1.0, v19
	v_add_f32_e32 v23, 1.0, v23
	v_rcp_f32_e32 v20, v20
	v_rcp_f32_e32 v16, v16
	v_rcp_f32_e32 v17, v17
	v_rcp_f32_e32 v22, v22
	v_rcp_f32_e32 v18, v18
	v_rcp_f32_e32 v19, v19
	v_rcp_f32_e32 v23, v23
	v_rcp_f32_e32 v21, v21
	s_nop 0
	v_cvt_pk_f16_f32 v19, v18, v19
	v_cvt_pk_f16_f32 v18, v16, v17
	v_cvt_pk_f16_f32 v17, v22, v23
	v_cvt_pk_f16_f32 v16, v20, v21
	global_store_dwordx4 v162, v[16:19], s[4:5] offset:256
	v_mul_f32_e32 v12, 0xbfb8aa3b, v12
	v_mul_f32_e32 v8, 0xbfb8aa3b, v8
	v_mul_f32_e32 v13, 0xbfb8aa3b, v13
	v_mul_f32_e32 v9, 0xbfb8aa3b, v9
	v_mul_f32_e32 v14, 0xbfb8aa3b, v14
	v_mul_f32_e32 v10, 0xbfb8aa3b, v10
	v_mul_f32_e32 v11, 0xbfb8aa3b, v11
	v_mul_f32_e32 v15, 0xbfb8aa3b, v15
	v_exp_f32_e32 v12, v12
	v_exp_f32_e32 v8, v8
	v_exp_f32_e32 v13, v13
	v_exp_f32_e32 v9, v9
	v_exp_f32_e32 v14, v14
	v_exp_f32_e32 v10, v10
	v_exp_f32_e32 v11, v11
	v_exp_f32_e32 v15, v15
	v_add_f32_e32 v12, 1.0, v12
	v_add_f32_e32 v8, 1.0, v8
	v_add_f32_e32 v13, 1.0, v13
	v_add_f32_e32 v9, 1.0, v9
	v_add_f32_e32 v14, 1.0, v14
	v_add_f32_e32 v10, 1.0, v10
	v_add_f32_e32 v11, 1.0, v11
	v_add_f32_e32 v15, 1.0, v15
	v_rcp_f32_e32 v12, v12
	v_rcp_f32_e32 v8, v8
	v_rcp_f32_e32 v9, v9
	v_rcp_f32_e32 v14, v14
	v_rcp_f32_e32 v10, v10
	v_rcp_f32_e32 v11, v11
	v_rcp_f32_e32 v15, v15
	v_rcp_f32_e32 v13, v13
	s_nop 0
	v_cvt_pk_f16_f32 v11, v10, v11
	v_cvt_pk_f16_f32 v10, v8, v9
	v_cvt_pk_f16_f32 v9, v14, v15
	v_cvt_pk_f16_f32 v8, v12, v13
	global_store_dwordx4 v163, v[8:11], s[4:5]
	v_mul_f32_e32 v4, 0xbfb8aa3b, v4
	v_mul_f32_e32 v0, 0xbfb8aa3b, v0
	v_mul_f32_e32 v5, 0xbfb8aa3b, v5
	v_mul_f32_e32 v1, 0xbfb8aa3b, v1
	v_mul_f32_e32 v6, 0xbfb8aa3b, v6
	v_mul_f32_e32 v2, 0xbfb8aa3b, v2
	v_mul_f32_e32 v3, 0xbfb8aa3b, v3
	v_mul_f32_e32 v7, 0xbfb8aa3b, v7
	v_exp_f32_e32 v4, v4
	v_exp_f32_e32 v0, v0
	v_exp_f32_e32 v5, v5
	v_exp_f32_e32 v1, v1
	v_exp_f32_e32 v6, v6
	v_exp_f32_e32 v2, v2
	v_exp_f32_e32 v3, v3
	v_exp_f32_e32 v7, v7
	v_add_f32_e32 v4, 1.0, v4
	v_add_f32_e32 v0, 1.0, v0
	v_add_f32_e32 v5, 1.0, v5
	v_add_f32_e32 v1, 1.0, v1
	v_add_f32_e32 v6, 1.0, v6
	v_add_f32_e32 v2, 1.0, v2
	v_add_f32_e32 v3, 1.0, v3
	v_add_f32_e32 v7, 1.0, v7
	v_rcp_f32_e32 v4, v4
	v_rcp_f32_e32 v0, v0
	v_rcp_f32_e32 v1, v1
	v_rcp_f32_e32 v6, v6
	v_rcp_f32_e32 v2, v2
	v_rcp_f32_e32 v3, v3
	v_rcp_f32_e32 v7, v7
	v_rcp_f32_e32 v5, v5
	s_nop 0
	v_cvt_pk_f16_f32 v3, v2, v3
	v_cvt_pk_f16_f32 v2, v0, v1
	v_cvt_pk_f16_f32 v1, v6, v7
	v_cvt_pk_f16_f32 v0, v4, v5
	global_store_dwordx4 v163, v[0:3], s[4:5] offset:256
	s_branch .LBB0_1145
.Lsh_k3:
	v_mov_b32_e32 v156, v136
	v_add_u32_e32 v157, 0x8000, v136
	v_add_u32_e32 v158, 0x10000, v136
	v_add_u32_e32 v159, 0x18000, v136
	v_add_u32_e32 v160, 0x40000, v136
	v_add_u32_e32 v161, 0x48000, v136
	v_add_u32_e32 v162, 0x50000, v136
	v_add_u32_e32 v163, 0x58000, v136
	global_load_dwordx4 v[164:167], v156, s[44:45]
	global_load_dwordx4 v[168:171], v156, s[44:45] offset:256
	global_load_dwordx4 v[172:175], v157, s[44:45]
	global_load_dwordx4 v[176:179], v157, s[44:45] offset:256
	global_load_dwordx4 v[180:183], v158, s[44:45]
	global_load_dwordx4 v[184:187], v158, s[44:45] offset:256
	global_load_dwordx4 v[188:191], v159, s[44:45]
	global_load_dwordx4 v[192:195], v159, s[44:45] offset:256
	s_waitcnt vmcnt(7)
	v_cvt_f32_f16_e32 v196, v164
	v_cvt_f32_f16_sdwa v197, v164 dst_sel:DWORD dst_unused:UNUSED_PAD src0_sel:WORD_1
	v_cvt_f32_f16_e32 v198, v165
	v_cvt_f32_f16_sdwa v199, v165 dst_sel:DWORD dst_unused:UNUSED_PAD src0_sel:WORD_1
	v_cvt_f32_f16_e32 v200, v166
	v_cvt_f32_f16_sdwa v201, v166 dst_sel:DWORD dst_unused:UNUSED_PAD src0_sel:WORD_1
	v_cvt_f32_f16_e32 v202, v167
	v_cvt_f32_f16_sdwa v203, v167 dst_sel:DWORD dst_unused:UNUSED_PAD src0_sel:WORD_1
	v_pk_mul_f32 v[124:125], v[124:125], v[196:197]
	v_pk_mul_f32 v[126:127], v[126:127], v[198:199]
	v_pk_mul_f32 v[120:121], v[120:121], v[200:201]
	v_pk_mul_f32 v[122:123], v[122:123], v[202:203]
	v_cvt_pk_f16_f32 v164, v124, v125
	v_cvt_pk_f16_f32 v165, v126, v127
	v_cvt_pk_f16_f32 v166, v120, v121
	v_cvt_pk_f16_f32 v167, v122, v123
	global_store_dwordx4 v156, v[164:167], s[44:45]
	s_nop 1
	global_load_dwordx4 v[164:167], v160, s[44:45]
	s_waitcnt vmcnt(8)
	v_cvt_f32_f16_e32 v196, v168
	v_cvt_f32_f16_sdwa v197, v168 dst_sel:DWORD dst_unused:UNUSED_PAD src0_sel:WORD_1
	v_cvt_f32_f16_e32 v198, v169
	v_cvt_f32_f16_sdwa v199, v169 dst_sel:DWORD dst_unused:UNUSED_PAD src0_sel:WORD_1
	v_cvt_f32_f16_e32 v200, v170
	v_cvt_f32_f16_sdwa v201, v170 dst_sel:DWORD dst_unused:UNUSED_PAD src0_sel:WORD_1
	v_cvt_f32_f16_e32 v202, v171
	v_cvt_f32_f16_sdwa v203, v171 dst_sel:DWORD dst_unused:UNUSED_PAD src0_sel:WORD_1
	v_pk_mul_f32 v[116:117], v[116:117], v[196:197]
	v_pk_mul_f32 v[118:119], v[118:119], v[198:199]
	v_pk_mul_f32 v[112:113], v[112:113], v[200:201]
	v_pk_mul_f32 v[114:115], v[114:115], v[202:203]
	v_cvt_pk_f16_f32 v168, v116, v117
	v_cvt_pk_f16_f32 v169, v118, v119
	v_cvt_pk_f16_f32 v170, v112, v113
	v_cvt_pk_f16_f32 v171, v114, v115
	global_store_dwordx4 v156, v[168:171], s[44:45] offset:256
	s_nop 1
	global_load_dwordx4 v[168:171], v160, s[44:45] offset:256
	s_waitcnt vmcnt(9)
	v_cvt_f32_f16_e32 v196, v172
	v_cvt_f32_f16_sdwa v197, v172 dst_sel:DWORD dst_unused:UNUSED_PAD src0_sel:WORD_1
	v_cvt_f32_f16_e32 v198, v173
	v_cvt_f32_f16_sdwa v199, v173 dst_sel:DWORD dst_unused:UNUSED_PAD src0_sel:WORD_1
	v_cvt_f32_f16_e32 v200, v174
	v_cvt_f32_f16_sdwa v201, v174 dst_sel:DWORD dst_unused:UNUSED_PAD src0_sel:WORD_1
	v_cvt_f32_f16_e32 v202, v175
	v_cvt_f32_f16_sdwa v203, v175 dst_sel:DWORD dst_unused:UNUSED_PAD src0_sel:WORD_1
	v_pk_mul_f32 v[108:109], v[108:109], v[196:197]
	v_pk_mul_f32 v[110:111], v[110:111], v[198:199]
	v_pk_mul_f32 v[104:105], v[104:105], v[200:201]
	v_pk_mul_f32 v[106:107], v[106:107], v[202:203]
	v_cvt_pk_f16_f32 v172, v108, v109
	v_cvt_pk_f16_f32 v173, v110, v111
	v_cvt_pk_f16_f32 v174, v104, v105
	v_cvt_pk_f16_f32 v175, v106, v107
	global_store_dwordx4 v157, v[172:175], s[44:45]
	s_nop 1
	global_load_dwordx4 v[172:175], v161, s[44:45]
	s_waitcnt vmcnt(10)
	v_cvt_f32_f16_e32 v196, v176
	v_cvt_f32_f16_sdwa v197, v176 dst_sel:DWORD dst_unused:UNUSED_PAD src0_sel:WORD_1
	v_cvt_f32_f16_e32 v198, v177
	v_cvt_f32_f16_sdwa v199, v177 dst_sel:DWORD dst_unused:UNUSED_PAD src0_sel:WORD_1
	v_cvt_f32_f16_e32 v200, v178
	v_cvt_f32_f16_sdwa v201, v178 dst_sel:DWORD dst_unused:UNUSED_PAD src0_sel:WORD_1
	v_cvt_f32_f16_e32 v202, v179
	v_cvt_f32_f16_sdwa v203, v179 dst_sel:DWORD dst_unused:UNUSED_PAD src0_sel:WORD_1
	v_pk_mul_f32 v[100:101], v[100:101], v[196:197]
	v_pk_mul_f32 v[102:103], v[102:103], v[198:199]
	v_pk_mul_f32 v[96:97], v[96:97], v[200:201]
	v_pk_mul_f32 v[98:99], v[98:99], v[202:203]
	v_cvt_pk_f16_f32 v176, v100, v101
	v_cvt_pk_f16_f32 v177, v102, v103
	v_cvt_pk_f16_f32 v178, v96, v97
	v_cvt_pk_f16_f32 v179, v98, v99
	global_store_dwordx4 v157, v[176:179], s[44:45] offset:256
	s_nop 1
	global_load_dwordx4 v[176:179], v161, s[44:45] offset:256
	s_waitcnt vmcnt(11)
	v_cvt_f32_f16_e32 v196, v180
	v_cvt_f32_f16_sdwa v197, v180 dst_sel:DWORD dst_unused:UNUSED_PAD src0_sel:WORD_1
	v_cvt_f32_f16_e32 v198, v181
	v_cvt_f32_f16_sdwa v199, v181 dst_sel:DWORD dst_unused:UNUSED_PAD src0_sel:WORD_1
	v_cvt_f32_f16_e32 v200, v182
	v_cvt_f32_f16_sdwa v201, v182 dst_sel:DWORD dst_unused:UNUSED_PAD src0_sel:WORD_1
	v_cvt_f32_f16_e32 v202, v183
	v_cvt_f32_f16_sdwa v203, v183 dst_sel:DWORD dst_unused:UNUSED_PAD src0_sel:WORD_1
	v_pk_mul_f32 v[92:93], v[92:93], v[196:197]
	v_pk_mul_f32 v[94:95], v[94:95], v[198:199]
	v_pk_mul_f32 v[88:89], v[88:89], v[200:201]
	v_pk_mul_f32 v[90:91], v[90:91], v[202:203]
	v_cvt_pk_f16_f32 v180, v92, v93
	v_cvt_pk_f16_f32 v181, v94, v95
	v_cvt_pk_f16_f32 v182, v88, v89
	v_cvt_pk_f16_f32 v183, v90, v91
	global_store_dwordx4 v158, v[180:183], s[44:45]
	s_nop 1
	global_load_dwordx4 v[180:183], v162, s[44:45]
	s_waitcnt vmcnt(12)
	v_cvt_f32_f16_e32 v196, v184
	v_cvt_f32_f16_sdwa v197, v184 dst_sel:DWORD dst_unused:UNUSED_PAD src0_sel:WORD_1
	v_cvt_f32_f16_e32 v198, v185
	v_cvt_f32_f16_sdwa v199, v185 dst_sel:DWORD dst_unused:UNUSED_PAD src0_sel:WORD_1
	v_cvt_f32_f16_e32 v200, v186
	v_cvt_f32_f16_sdwa v201, v186 dst_sel:DWORD dst_unused:UNUSED_PAD src0_sel:WORD_1
	v_cvt_f32_f16_e32 v202, v187
	v_cvt_f32_f16_sdwa v203, v187 dst_sel:DWORD dst_unused:UNUSED_PAD src0_sel:WORD_1
	v_pk_mul_f32 v[84:85], v[84:85], v[196:197]
	v_pk_mul_f32 v[86:87], v[86:87], v[198:199]
	v_pk_mul_f32 v[80:81], v[80:81], v[200:201]
	v_pk_mul_f32 v[82:83], v[82:83], v[202:203]
	v_cvt_pk_f16_f32 v184, v84, v85
	v_cvt_pk_f16_f32 v185, v86, v87
	v_cvt_pk_f16_f32 v186, v80, v81
	v_cvt_pk_f16_f32 v187, v82, v83
	global_store_dwordx4 v158, v[184:187], s[44:45] offset:256
	s_nop 1
	global_load_dwordx4 v[184:187], v162, s[44:45] offset:256
	s_waitcnt vmcnt(13)
	v_cvt_f32_f16_e32 v196, v188
	v_cvt_f32_f16_sdwa v197, v188 dst_sel:DWORD dst_unused:UNUSED_PAD src0_sel:WORD_1
	v_cvt_f32_f16_e32 v198, v189
	v_cvt_f32_f16_sdwa v199, v189 dst_sel:DWORD dst_unused:UNUSED_PAD src0_sel:WORD_1
	v_cvt_f32_f16_e32 v200, v190
	v_cvt_f32_f16_sdwa v201, v190 dst_sel:DWORD dst_unused:UNUSED_PAD src0_sel:WORD_1
	v_cvt_f32_f16_e32 v202, v191
	v_cvt_f32_f16_sdwa v203, v191 dst_sel:DWORD dst_unused:UNUSED_PAD src0_sel:WORD_1
	v_pk_mul_f32 v[76:77], v[76:77], v[196:197]
	v_pk_mul_f32 v[78:79], v[78:79], v[198:199]
	v_pk_mul_f32 v[72:73], v[72:73], v[200:201]
	v_pk_mul_f32 v[74:75], v[74:75], v[202:203]
	v_cvt_pk_f16_f32 v188, v76, v77
	v_cvt_pk_f16_f32 v189, v78, v79
	v_cvt_pk_f16_f32 v190, v72, v73
	v_cvt_pk_f16_f32 v191, v74, v75
	global_store_dwordx4 v159, v[188:191], s[44:45]
	s_nop 1
	global_load_dwordx4 v[188:191], v163, s[44:45]
	s_waitcnt vmcnt(14)
	v_cvt_f32_f16_e32 v196, v192
	v_cvt_f32_f16_sdwa v197, v192 dst_sel:DWORD dst_unused:UNUSED_PAD src0_sel:WORD_1
	v_cvt_f32_f16_e32 v198, v193
	v_cvt_f32_f16_sdwa v199, v193 dst_sel:DWORD dst_unused:UNUSED_PAD src0_sel:WORD_1
	v_cvt_f32_f16_e32 v200, v194
	v_cvt_f32_f16_sdwa v201, v194 dst_sel:DWORD dst_unused:UNUSED_PAD src0_sel:WORD_1
	v_cvt_f32_f16_e32 v202, v195
	v_cvt_f32_f16_sdwa v203, v195 dst_sel:DWORD dst_unused:UNUSED_PAD src0_sel:WORD_1
	v_pk_mul_f32 v[68:69], v[68:69], v[196:197]
	v_pk_mul_f32 v[70:71], v[70:71], v[198:199]
	v_pk_mul_f32 v[64:65], v[64:65], v[200:201]
	v_pk_mul_f32 v[66:67], v[66:67], v[202:203]
	v_cvt_pk_f16_f32 v192, v68, v69
	v_cvt_pk_f16_f32 v193, v70, v71
	v_cvt_pk_f16_f32 v194, v64, v65
	v_cvt_pk_f16_f32 v195, v66, v67
	global_store_dwordx4 v159, v[192:195], s[44:45] offset:256
	s_nop 1
	global_load_dwordx4 v[192:195], v163, s[44:45] offset:256
	s_waitcnt vmcnt(14)
	v_cvt_f32_f16_e32 v196, v164
	v_cvt_f32_f16_sdwa v197, v164 dst_sel:DWORD dst_unused:UNUSED_PAD src0_sel:WORD_1
	v_cvt_f32_f16_e32 v198, v165
	v_cvt_f32_f16_sdwa v199, v165 dst_sel:DWORD dst_unused:UNUSED_PAD src0_sel:WORD_1
	v_cvt_f32_f16_e32 v200, v166
	v_cvt_f32_f16_sdwa v201, v166 dst_sel:DWORD dst_unused:UNUSED_PAD src0_sel:WORD_1
	v_cvt_f32_f16_e32 v202, v167
	v_cvt_f32_f16_sdwa v203, v167 dst_sel:DWORD dst_unused:UNUSED_PAD src0_sel:WORD_1
	v_pk_mul_f32 v[60:61], v[60:61], v[196:197]
	v_pk_mul_f32 v[62:63], v[62:63], v[198:199]
	v_pk_mul_f32 v[56:57], v[56:57], v[200:201]
	v_pk_mul_f32 v[58:59], v[58:59], v[202:203]
	v_cvt_pk_f16_f32 v164, v60, v61
	v_cvt_pk_f16_f32 v165, v62, v63
	v_cvt_pk_f16_f32 v166, v56, v57
	v_cvt_pk_f16_f32 v167, v58, v59
	global_store_dwordx4 v160, v[164:167], s[44:45]
	s_nop 1
	s_waitcnt vmcnt(13)
	v_cvt_f32_f16_e32 v196, v168
	v_cvt_f32_f16_sdwa v197, v168 dst_sel:DWORD dst_unused:UNUSED_PAD src0_sel:WORD_1
	v_cvt_f32_f16_e32 v198, v169
	v_cvt_f32_f16_sdwa v199, v169 dst_sel:DWORD dst_unused:UNUSED_PAD src0_sel:WORD_1
	v_cvt_f32_f16_e32 v200, v170
	v_cvt_f32_f16_sdwa v201, v170 dst_sel:DWORD dst_unused:UNUSED_PAD src0_sel:WORD_1
	v_cvt_f32_f16_e32 v202, v171
	v_cvt_f32_f16_sdwa v203, v171 dst_sel:DWORD dst_unused:UNUSED_PAD src0_sel:WORD_1
	v_pk_mul_f32 v[52:53], v[52:53], v[196:197]
	v_pk_mul_f32 v[54:55], v[54:55], v[198:199]
	v_pk_mul_f32 v[48:49], v[48:49], v[200:201]
	v_pk_mul_f32 v[50:51], v[50:51], v[202:203]
	v_cvt_pk_f16_f32 v168, v52, v53
	v_cvt_pk_f16_f32 v169, v54, v55
	v_cvt_pk_f16_f32 v170, v48, v49
	v_cvt_pk_f16_f32 v171, v50, v51
	global_store_dwordx4 v160, v[168:171], s[44:45] offset:256
	s_nop 1
	s_waitcnt vmcnt(12)
	v_cvt_f32_f16_e32 v196, v172
	v_cvt_f32_f16_sdwa v197, v172 dst_sel:DWORD dst_unused:UNUSED_PAD src0_sel:WORD_1
	v_cvt_f32_f16_e32 v198, v173
	v_cvt_f32_f16_sdwa v199, v173 dst_sel:DWORD dst_unused:UNUSED_PAD src0_sel:WORD_1
	v_cvt_f32_f16_e32 v200, v174
	v_cvt_f32_f16_sdwa v201, v174 dst_sel:DWORD dst_unused:UNUSED_PAD src0_sel:WORD_1
	v_cvt_f32_f16_e32 v202, v175
	v_cvt_f32_f16_sdwa v203, v175 dst_sel:DWORD dst_unused:UNUSED_PAD src0_sel:WORD_1
	v_pk_mul_f32 v[44:45], v[44:45], v[196:197]
	v_pk_mul_f32 v[46:47], v[46:47], v[198:199]
	v_pk_mul_f32 v[40:41], v[40:41], v[200:201]
	v_pk_mul_f32 v[42:43], v[42:43], v[202:203]
	v_cvt_pk_f16_f32 v172, v44, v45
	v_cvt_pk_f16_f32 v173, v46, v47
	v_cvt_pk_f16_f32 v174, v40, v41
	v_cvt_pk_f16_f32 v175, v42, v43
	global_store_dwordx4 v161, v[172:175], s[44:45]
	s_nop 1
	s_waitcnt vmcnt(11)
	v_cvt_f32_f16_e32 v196, v176
	v_cvt_f32_f16_sdwa v197, v176 dst_sel:DWORD dst_unused:UNUSED_PAD src0_sel:WORD_1
	v_cvt_f32_f16_e32 v198, v177
	v_cvt_f32_f16_sdwa v199, v177 dst_sel:DWORD dst_unused:UNUSED_PAD src0_sel:WORD_1
	v_cvt_f32_f16_e32 v200, v178
	v_cvt_f32_f16_sdwa v201, v178 dst_sel:DWORD dst_unused:UNUSED_PAD src0_sel:WORD_1
	v_cvt_f32_f16_e32 v202, v179
	v_cvt_f32_f16_sdwa v203, v179 dst_sel:DWORD dst_unused:UNUSED_PAD src0_sel:WORD_1
	v_pk_mul_f32 v[36:37], v[36:37], v[196:197]
	v_pk_mul_f32 v[38:39], v[38:39], v[198:199]
	v_pk_mul_f32 v[32:33], v[32:33], v[200:201]
	v_pk_mul_f32 v[34:35], v[34:35], v[202:203]
	v_cvt_pk_f16_f32 v176, v36, v37
	v_cvt_pk_f16_f32 v177, v38, v39
	v_cvt_pk_f16_f32 v178, v32, v33
	v_cvt_pk_f16_f32 v179, v34, v35
	global_store_dwordx4 v161, v[176:179], s[44:45] offset:256
	s_nop 1
	s_waitcnt vmcnt(10)
	v_cvt_f32_f16_e32 v196, v180
	v_cvt_f32_f16_sdwa v197, v180 dst_sel:DWORD dst_unused:UNUSED_PAD src0_sel:WORD_1
	v_cvt_f32_f16_e32 v198, v181
	v_cvt_f32_f16_sdwa v199, v181 dst_sel:DWORD dst_unused:UNUSED_PAD src0_sel:WORD_1
	v_cvt_f32_f16_e32 v200, v182
	v_cvt_f32_f16_sdwa v201, v182 dst_sel:DWORD dst_unused:UNUSED_PAD src0_sel:WORD_1
	v_cvt_f32_f16_e32 v202, v183
	v_cvt_f32_f16_sdwa v203, v183 dst_sel:DWORD dst_unused:UNUSED_PAD src0_sel:WORD_1
	v_pk_mul_f32 v[28:29], v[28:29], v[196:197]
	v_pk_mul_f32 v[30:31], v[30:31], v[198:199]
	v_pk_mul_f32 v[24:25], v[24:25], v[200:201]
	v_pk_mul_f32 v[26:27], v[26:27], v[202:203]
	v_cvt_pk_f16_f32 v180, v28, v29
	v_cvt_pk_f16_f32 v181, v30, v31
	v_cvt_pk_f16_f32 v182, v24, v25
	v_cvt_pk_f16_f32 v183, v26, v27
	global_store_dwordx4 v162, v[180:183], s[44:45]
	s_nop 1
	s_waitcnt vmcnt(9)
	v_cvt_f32_f16_e32 v196, v184
	v_cvt_f32_f16_sdwa v197, v184 dst_sel:DWORD dst_unused:UNUSED_PAD src0_sel:WORD_1
	v_cvt_f32_f16_e32 v198, v185
	v_cvt_f32_f16_sdwa v199, v185 dst_sel:DWORD dst_unused:UNUSED_PAD src0_sel:WORD_1
	v_cvt_f32_f16_e32 v200, v186
	v_cvt_f32_f16_sdwa v201, v186 dst_sel:DWORD dst_unused:UNUSED_PAD src0_sel:WORD_1
	v_cvt_f32_f16_e32 v202, v187
	v_cvt_f32_f16_sdwa v203, v187 dst_sel:DWORD dst_unused:UNUSED_PAD src0_sel:WORD_1
	v_pk_mul_f32 v[20:21], v[20:21], v[196:197]
	v_pk_mul_f32 v[22:23], v[22:23], v[198:199]
	v_pk_mul_f32 v[16:17], v[16:17], v[200:201]
	v_pk_mul_f32 v[18:19], v[18:19], v[202:203]
	v_cvt_pk_f16_f32 v184, v20, v21
	v_cvt_pk_f16_f32 v185, v22, v23
	v_cvt_pk_f16_f32 v186, v16, v17
	v_cvt_pk_f16_f32 v187, v18, v19
	global_store_dwordx4 v162, v[184:187], s[44:45] offset:256
	s_nop 1
	s_waitcnt vmcnt(8)
	v_cvt_f32_f16_e32 v196, v188
	v_cvt_f32_f16_sdwa v197, v188 dst_sel:DWORD dst_unused:UNUSED_PAD src0_sel:WORD_1
	v_cvt_f32_f16_e32 v198, v189
	v_cvt_f32_f16_sdwa v199, v189 dst_sel:DWORD dst_unused:UNUSED_PAD src0_sel:WORD_1
	v_cvt_f32_f16_e32 v200, v190
	v_cvt_f32_f16_sdwa v201, v190 dst_sel:DWORD dst_unused:UNUSED_PAD src0_sel:WORD_1
	v_cvt_f32_f16_e32 v202, v191
	v_cvt_f32_f16_sdwa v203, v191 dst_sel:DWORD dst_unused:UNUSED_PAD src0_sel:WORD_1
	v_pk_mul_f32 v[12:13], v[12:13], v[196:197]
	v_pk_mul_f32 v[14:15], v[14:15], v[198:199]
	v_pk_mul_f32 v[8:9], v[8:9], v[200:201]
	v_pk_mul_f32 v[10:11], v[10:11], v[202:203]
	v_cvt_pk_f16_f32 v188, v12, v13
	v_cvt_pk_f16_f32 v189, v14, v15
	v_cvt_pk_f16_f32 v190, v8, v9
	v_cvt_pk_f16_f32 v191, v10, v11
	global_store_dwordx4 v163, v[188:191], s[44:45]
	s_nop 1
	s_waitcnt vmcnt(7)
	v_cvt_f32_f16_e32 v196, v192
	v_cvt_f32_f16_sdwa v197, v192 dst_sel:DWORD dst_unused:UNUSED_PAD src0_sel:WORD_1
	v_cvt_f32_f16_e32 v198, v193
	v_cvt_f32_f16_sdwa v199, v193 dst_sel:DWORD dst_unused:UNUSED_PAD src0_sel:WORD_1
	v_cvt_f32_f16_e32 v200, v194
	v_cvt_f32_f16_sdwa v201, v194 dst_sel:DWORD dst_unused:UNUSED_PAD src0_sel:WORD_1
	v_cvt_f32_f16_e32 v202, v195
	v_cvt_f32_f16_sdwa v203, v195 dst_sel:DWORD dst_unused:UNUSED_PAD src0_sel:WORD_1
	v_pk_mul_f32 v[4:5], v[4:5], v[196:197]
	v_pk_mul_f32 v[6:7], v[6:7], v[198:199]
	v_pk_mul_f32 v[0:1], v[0:1], v[200:201]
	v_pk_mul_f32 v[2:3], v[2:3], v[202:203]
	v_cvt_pk_f16_f32 v192, v4, v5
	v_cvt_pk_f16_f32 v193, v6, v7
	v_cvt_pk_f16_f32 v194, v0, v1
	v_cvt_pk_f16_f32 v195, v2, v3
	global_store_dwordx4 v163, v[192:195], s[44:45] offset:256
	s_nop 1
	s_branch .LBB0_1145
